# final norm row loop software-pipelined too (next row's 12 loads issued before reducing the current row)
# baseline (speedup 1.0000x reference)
.LBB0_20:
	v_mov_b64_e32 v[100:101], v[66:67]
	global_load_dwordx2 v[80:81], v[64:65], off nt
	global_load_dwordx2 v[68:69], v[64:65], off offset:512 nt
	global_load_dwordx4 v[52:55], v[100:101], off offset:-3072 nt
	global_load_dwordx4 v[48:51], v[100:101], off offset:-2048 nt
	global_load_dwordx2 v[70:71], v[64:65], off offset:1024 nt
	global_load_dwordx4 v[60:63], v[100:101], off offset:-1024 nt
	global_load_dwordx4 v[56:59], v[100:101], off nt
	global_load_dwordx2 v[82:83], v[64:65], off offset:1536 nt
	v_add_co_u32_e32 v84, vcc, 0xec800000, v64
	v_add_co_u32_e64 v86, s[0:1], s60, v64
	s_nop 0
	v_addc_co_u32_e32 v85, vcc, -1, v65, vcc
	v_addc_co_u32_e64 v87, s[0:1], -1, v65, s[0:1]
	global_load_dwordx2 v[84:85], v[84:85], off nt
	s_nop 0
	global_load_dwordx2 v[88:89], v[86:87], off offset:-3584 nt
	global_load_dwordx2 v[90:91], v[86:87], off offset:-3072 nt
	s_nop 0
	global_load_dwordx2 v[86:87], v[86:87], off offset:-2560 nt
	v_add_u32_e32 v79, 32, v79
	v_cmp_ge_i32_e32 vcc, v79, v72
	s_or_b64 s[16:17], vcc, s[16:17]
	v_lshl_add_u64 v[64:65], v[64:65], 0, s[12:13]
	v_lshl_add_u64 v[100:101], v[100:101], 0, s[14:15]
	s_cmp_eq_u64 s[16:17], 0
	s_cbranch_scc0 .Lpn_f_nf
	global_load_dwordx2 v[180:181], v[64:65], off nt
	global_load_dwordx2 v[168:169], v[64:65], off offset:512 nt
	global_load_dwordx4 v[152:155], v[100:101], off offset:-3072 nt
	global_load_dwordx4 v[148:151], v[100:101], off offset:-2048 nt
	global_load_dwordx2 v[170:171], v[64:65], off offset:1024 nt
	global_load_dwordx4 v[160:163], v[100:101], off offset:-1024 nt
	global_load_dwordx4 v[156:159], v[100:101], off nt
	global_load_dwordx2 v[182:183], v[64:65], off offset:1536 nt
	v_add_co_u32_e32 v184, vcc, 0xec800000, v64
	v_add_co_u32_e64 v186, s[0:1], s60, v64
	s_nop 0
	v_addc_co_u32_e32 v185, vcc, -1, v65, vcc
	v_addc_co_u32_e64 v187, s[0:1], -1, v65, s[0:1]
	global_load_dwordx2 v[184:185], v[184:185], off nt
	s_nop 0
	global_load_dwordx2 v[188:189], v[186:187], off offset:-3584 nt
	global_load_dwordx2 v[190:191], v[186:187], off offset:-3072 nt
	s_nop 0
	global_load_dwordx2 v[186:187], v[186:187], off offset:-2560 nt
	s_waitcnt vmcnt(12)
	s_branch .Lpn_f_ga

.Lpn_f_ga:
	v_lshlrev_b32_e32 v92, 16, v80
	v_and_b32_e32 v93, 0xffff0000, v80
	v_lshlrev_b32_e32 v80, 16, v81
	v_and_b32_e32 v81, 0xffff0000, v81
	v_lshlrev_b32_e32 v94, 16, v68
	v_and_b32_e32 v95, 0xffff0000, v68
	v_lshlrev_b32_e32 v68, 16, v69
	v_and_b32_e32 v69, 0xffff0000, v69
	v_lshlrev_b32_e32 v96, 16, v70
	v_and_b32_e32 v97, 0xffff0000, v70
	v_lshlrev_b32_e32 v70, 16, v71
	v_and_b32_e32 v71, 0xffff0000, v71
	v_lshlrev_b32_e32 v98, 16, v82
	v_and_b32_e32 v99, 0xffff0000, v82
	v_lshlrev_b32_e32 v82, 16, v83
	v_and_b32_e32 v83, 0xffff0000, v83
	v_pk_fma_f32 v[52:53], v[44:45], v[92:93], v[52:53]
	v_pk_fma_f32 v[54:55], v[46:47], v[80:81], v[54:55]
	v_pk_fma_f32 v[48:49], v[40:41], v[94:95], v[48:49]
	v_pk_fma_f32 v[50:51], v[42:43], v[68:69], v[50:51]
	v_pk_fma_f32 v[62:63], v[30:31], v[70:71], v[62:63]
	v_pk_fma_f32 v[58:59], v[26:27], v[82:83], v[58:59]
	v_lshlrev_b32_e32 v68, 16, v84
	v_and_b32_e32 v69, 0xffff0000, v84
	v_lshlrev_b32_e32 v70, 16, v85
	v_and_b32_e32 v71, 0xffff0000, v85
	v_lshlrev_b32_e32 v80, 16, v88
	v_and_b32_e32 v81, 0xffff0000, v88
	v_lshlrev_b32_e32 v82, 16, v89
	v_and_b32_e32 v83, 0xffff0000, v89
	v_pk_fma_f32 v[52:53], v[36:37], v[68:69], v[52:53]
	v_pk_fma_f32 v[54:55], v[38:39], v[70:71], v[54:55]
	v_pk_fma_f32 v[48:49], v[32:33], v[80:81], v[48:49]
	v_pk_fma_f32 v[50:51], v[34:35], v[82:83], v[50:51]
	v_pk_fma_f32 v[60:61], v[28:29], v[96:97], v[60:61]
	v_lshlrev_b32_e32 v84, 16, v90
	v_and_b32_e32 v85, 0xffff0000, v90
	v_lshlrev_b32_e32 v88, 16, v91
	v_and_b32_e32 v89, 0xffff0000, v91
	v_mov_b32_e32 v70, v53
	v_mov_b32_e32 v71, v55
	v_mov_b32_e32 v82, v49
	v_mov_b32_e32 v83, v51
	v_pk_fma_f32 v[56:57], v[24:25], v[98:99], v[56:57]
	v_lshlrev_b32_e32 v90, 16, v86
	v_and_b32_e32 v91, 0xffff0000, v86
	v_lshlrev_b32_e32 v86, 16, v87
	v_and_b32_e32 v87, 0xffff0000, v87
	v_pk_fma_f32 v[60:61], v[20:21], v[84:85], v[60:61]
	v_pk_fma_f32 v[62:63], v[22:23], v[88:89], v[62:63]
	v_mov_b32_e32 v68, v52
	v_mov_b32_e32 v69, v54
	v_mov_b32_e32 v80, v48
	v_mov_b32_e32 v81, v50
	v_pk_mul_f32 v[70:71], v[70:71], v[70:71]
	v_pk_mul_f32 v[82:83], v[82:83], v[82:83]
	v_pk_fma_f32 v[56:57], v[16:17], v[90:91], v[56:57]
	v_pk_fma_f32 v[58:59], v[18:19], v[86:87], v[58:59]
	v_mul_f32_e32 v84, v61, v61
	v_mul_f32_e32 v86, v63, v63
	v_pk_fma_f32 v[68:69], v[68:69], v[68:69], v[70:71]
	v_pk_fma_f32 v[70:71], v[80:81], v[80:81], v[82:83]
	v_pk_mul_f32 v[88:89], v[56:57], v[56:57]
	v_pk_mul_f32 v[90:91], v[58:59], v[58:59]
	v_pk_fma_f32 v[84:85], v[60:61], v[60:61], v[84:85] op_sel_hi:[1,1,0]
	v_pk_fma_f32 v[86:87], v[62:63], v[62:63], v[86:87] op_sel_hi:[1,1,0]
	v_pk_add_f32 v[68:69], v[68:69], v[68:69] op_sel:[0,1] op_sel_hi:[1,0]
	v_pk_add_f32 v[70:71], v[70:71], v[70:71] op_sel:[0,1] op_sel_hi:[1,0]
	v_mov_b32_e32 v85, v90
	v_mov_b32_e32 v87, v91
	v_mov_b32_e32 v69, v88
	v_mov_b32_e32 v71, v89
	v_pk_add_f32 v[80:81], v[84:85], v[86:87]
	v_pk_add_f32 v[68:69], v[68:69], v[70:71]
	s_nop 0
	v_pk_add_f32 v[68:69], v[68:69], v[80:81]
	s_nop 0
	v_add_f32_e32 v68, v68, v69
	ds_bpermute_b32 v69, v73, v68
	s_waitcnt lgkmcnt(0)
	v_add_f32_e32 v68, v68, v69
	ds_bpermute_b32 v69, v74, v68
	s_waitcnt lgkmcnt(0)
	v_add_f32_e32 v68, v68, v69
	ds_bpermute_b32 v69, v75, v68
	s_waitcnt lgkmcnt(0)
	v_add_f32_e32 v68, v68, v69
	ds_bpermute_b32 v69, v76, v68
	s_waitcnt lgkmcnt(0)
	v_add_f32_e32 v68, v68, v69
	ds_bpermute_b32 v69, v77, v68
	s_waitcnt lgkmcnt(0)
	v_add_f32_e32 v68, v68, v69
	ds_bpermute_b32 v69, v78, v68
	s_waitcnt lgkmcnt(0)
	v_add_f32_e32 v68, v68, v69
	v_fmamk_f32 v68, v68, 0x3a800000, v201
	v_mul_f32_e32 v69, 0x4b800000, v68
	v_cmp_gt_f32_e32 vcc, s20, v68
	s_nop 1
	v_cndmask_b32_e32 v68, v68, v69, vcc
	v_rsq_f32_e32 v68, v68
	s_nop 0
	v_mul_f32_e32 v69, 0x45800000, v68
	v_cndmask_b32_e32 v68, v68, v69, vcc
	v_pk_mul_f32 v[52:53], v[52:53], v[68:69] op_sel_hi:[1,0]
	v_pk_mul_f32 v[54:55], v[54:55], v[68:69] op_sel_hi:[1,0]
	v_pk_mul_f32 v[70:71], v[48:49], v[68:69] op_sel_hi:[1,0]
	v_pk_mul_f32 v[80:81], v[50:51], v[68:69] op_sel_hi:[1,0]
	v_pk_mul_f32 v[60:61], v[60:61], v[68:69] op_sel_hi:[1,0]
	v_pk_mul_f32 v[62:63], v[62:63], v[68:69] op_sel_hi:[1,0]
	v_pk_mul_f32 v[82:83], v[56:57], v[68:69] op_sel_hi:[1,0]
	v_pk_mul_f32 v[68:69], v[58:59], v[68:69] op_sel_hi:[1,0]
	v_pk_mul_f32 v[50:51], v[2:3], v[54:55]
	v_pk_mul_f32 v[48:49], v[0:1], v[52:53]
	v_pk_mul_f32 v[54:55], v[6:7], v[80:81]
	v_pk_mul_f32 v[52:53], v[4:5], v[70:71]
	v_pk_mul_f32 v[58:59], v[10:11], v[62:63]
	v_pk_mul_f32 v[56:57], v[8:9], v[60:61]
	v_pk_mul_f32 v[62:63], v[14:15], v[68:69]
	v_pk_mul_f32 v[60:61], v[12:13], v[82:83]
	global_store_dwordx4 v[66:67], v[48:51], off offset:-3072 nt
	global_store_dwordx4 v[66:67], v[52:55], off offset:-2048 nt
	global_store_dwordx4 v[66:67], v[56:59], off offset:-1024 nt
	global_store_dwordx4 v[66:67], v[60:63], off nt
	v_lshl_add_u64 v[66:67], v[66:67], 0, s[14:15]
	s_cmp_eq_u64 s[16:17], 0
	s_cbranch_scc0 .Lpn_f_done
	v_add_u32_e32 v79, 32, v79
	v_cmp_ge_i32_e32 vcc, v79, v72
	s_or_b64 s[16:17], vcc, s[16:17]
	v_lshl_add_u64 v[64:65], v[64:65], 0, s[12:13]
	v_lshl_add_u64 v[100:101], v[100:101], 0, s[14:15]
	s_cmp_eq_u64 s[16:17], 0
	s_cbranch_scc0 .Lpn_f_nb
	global_load_dwordx2 v[80:81], v[64:65], off nt
	global_load_dwordx2 v[68:69], v[64:65], off offset:512 nt
	global_load_dwordx4 v[52:55], v[100:101], off offset:-3072 nt
	global_load_dwordx4 v[48:51], v[100:101], off offset:-2048 nt
	global_load_dwordx2 v[70:71], v[64:65], off offset:1024 nt
	global_load_dwordx4 v[60:63], v[100:101], off offset:-1024 nt
	global_load_dwordx4 v[56:59], v[100:101], off nt
	global_load_dwordx2 v[82:83], v[64:65], off offset:1536 nt
	v_add_co_u32_e32 v84, vcc, 0xec800000, v64
	v_add_co_u32_e64 v86, s[0:1], s60, v64
	s_nop 0
	v_addc_co_u32_e32 v85, vcc, -1, v65, vcc
	v_addc_co_u32_e64 v87, s[0:1], -1, v65, s[0:1]
	global_load_dwordx2 v[84:85], v[84:85], off nt
	s_nop 0
	global_load_dwordx2 v[88:89], v[86:87], off offset:-3584 nt
	global_load_dwordx2 v[90:91], v[86:87], off offset:-3072 nt
	s_nop 0
	global_load_dwordx2 v[86:87], v[86:87], off offset:-2560 nt
	s_waitcnt vmcnt(16)
	s_branch .Lpn_f_gb

.Lpn_f_gb:
	v_lshlrev_b32_e32 v92, 16, v180
	v_and_b32_e32 v93, 0xffff0000, v180
	v_lshlrev_b32_e32 v180, 16, v181
	v_and_b32_e32 v181, 0xffff0000, v181
	v_lshlrev_b32_e32 v94, 16, v168
	v_and_b32_e32 v95, 0xffff0000, v168
	v_lshlrev_b32_e32 v168, 16, v169
	v_and_b32_e32 v169, 0xffff0000, v169
	v_lshlrev_b32_e32 v96, 16, v170
	v_and_b32_e32 v97, 0xffff0000, v170
	v_lshlrev_b32_e32 v170, 16, v171
	v_and_b32_e32 v171, 0xffff0000, v171
	v_lshlrev_b32_e32 v98, 16, v182
	v_and_b32_e32 v99, 0xffff0000, v182
	v_lshlrev_b32_e32 v182, 16, v183
	v_and_b32_e32 v183, 0xffff0000, v183
	v_pk_fma_f32 v[152:153], v[44:45], v[92:93], v[152:153]
	v_pk_fma_f32 v[154:155], v[46:47], v[180:181], v[154:155]
	v_pk_fma_f32 v[148:149], v[40:41], v[94:95], v[148:149]
	v_pk_fma_f32 v[150:151], v[42:43], v[168:169], v[150:151]
	v_pk_fma_f32 v[162:163], v[30:31], v[170:171], v[162:163]
	v_pk_fma_f32 v[158:159], v[26:27], v[182:183], v[158:159]
	v_lshlrev_b32_e32 v168, 16, v184
	v_and_b32_e32 v169, 0xffff0000, v184
	v_lshlrev_b32_e32 v170, 16, v185
	v_and_b32_e32 v171, 0xffff0000, v185
	v_lshlrev_b32_e32 v180, 16, v188
	v_and_b32_e32 v181, 0xffff0000, v188
	v_lshlrev_b32_e32 v182, 16, v189
	v_and_b32_e32 v183, 0xffff0000, v189
	v_pk_fma_f32 v[152:153], v[36:37], v[168:169], v[152:153]
	v_pk_fma_f32 v[154:155], v[38:39], v[170:171], v[154:155]
	v_pk_fma_f32 v[148:149], v[32:33], v[180:181], v[148:149]
	v_pk_fma_f32 v[150:151], v[34:35], v[182:183], v[150:151]
	v_pk_fma_f32 v[160:161], v[28:29], v[96:97], v[160:161]
	v_lshlrev_b32_e32 v184, 16, v190
	v_and_b32_e32 v185, 0xffff0000, v190
	v_lshlrev_b32_e32 v188, 16, v191
	v_and_b32_e32 v189, 0xffff0000, v191
	v_mov_b32_e32 v170, v153
	v_mov_b32_e32 v171, v155
	v_mov_b32_e32 v182, v149
	v_mov_b32_e32 v183, v151
	v_pk_fma_f32 v[156:157], v[24:25], v[98:99], v[156:157]
	v_lshlrev_b32_e32 v190, 16, v186
	v_and_b32_e32 v191, 0xffff0000, v186
	v_lshlrev_b32_e32 v186, 16, v187
	v_and_b32_e32 v187, 0xffff0000, v187
	v_pk_fma_f32 v[160:161], v[20:21], v[184:185], v[160:161]
	v_pk_fma_f32 v[162:163], v[22:23], v[188:189], v[162:163]
	v_mov_b32_e32 v168, v152
	v_mov_b32_e32 v169, v154
	v_mov_b32_e32 v180, v148
	v_mov_b32_e32 v181, v150
	v_pk_mul_f32 v[170:171], v[170:171], v[170:171]
	v_pk_mul_f32 v[182:183], v[182:183], v[182:183]
	v_pk_fma_f32 v[156:157], v[16:17], v[190:191], v[156:157]
	v_pk_fma_f32 v[158:159], v[18:19], v[186:187], v[158:159]
	v_mul_f32_e32 v184, v161, v161
	v_mul_f32_e32 v186, v163, v163
	v_pk_fma_f32 v[168:169], v[168:169], v[168:169], v[170:171]
	v_pk_fma_f32 v[170:171], v[180:181], v[180:181], v[182:183]
	v_pk_mul_f32 v[188:189], v[156:157], v[156:157]
	v_pk_mul_f32 v[190:191], v[158:159], v[158:159]
	v_pk_fma_f32 v[184:185], v[160:161], v[160:161], v[184:185] op_sel_hi:[1,1,0]
	v_pk_fma_f32 v[186:187], v[162:163], v[162:163], v[186:187] op_sel_hi:[1,1,0]
	v_pk_add_f32 v[168:169], v[168:169], v[168:169] op_sel:[0,1] op_sel_hi:[1,0]
	v_pk_add_f32 v[170:171], v[170:171], v[170:171] op_sel:[0,1] op_sel_hi:[1,0]
	v_mov_b32_e32 v185, v190
	v_mov_b32_e32 v187, v191
	v_mov_b32_e32 v169, v188
	v_mov_b32_e32 v171, v189
	v_pk_add_f32 v[180:181], v[184:185], v[186:187]
	v_pk_add_f32 v[168:169], v[168:169], v[170:171]
	s_nop 0
	v_pk_add_f32 v[168:169], v[168:169], v[180:181]
	s_nop 0
	v_add_f32_e32 v168, v168, v169
	ds_bpermute_b32 v169, v73, v168
	s_waitcnt lgkmcnt(0)
	v_add_f32_e32 v168, v168, v169
	ds_bpermute_b32 v169, v74, v168
	s_waitcnt lgkmcnt(0)
	v_add_f32_e32 v168, v168, v169
	ds_bpermute_b32 v169, v75, v168
	s_waitcnt lgkmcnt(0)
	v_add_f32_e32 v168, v168, v169
	ds_bpermute_b32 v169, v76, v168
	s_waitcnt lgkmcnt(0)
	v_add_f32_e32 v168, v168, v169
	ds_bpermute_b32 v169, v77, v168
	s_waitcnt lgkmcnt(0)
	v_add_f32_e32 v168, v168, v169
	ds_bpermute_b32 v169, v78, v168
	s_waitcnt lgkmcnt(0)
	v_add_f32_e32 v168, v168, v169
	v_fmamk_f32 v168, v168, 0x3a800000, v201
	v_mul_f32_e32 v169, 0x4b800000, v168
	v_cmp_gt_f32_e32 vcc, s20, v168
	s_nop 1
	v_cndmask_b32_e32 v168, v168, v169, vcc
	v_rsq_f32_e32 v168, v168
	s_nop 0
	v_mul_f32_e32 v169, 0x45800000, v168
	v_cndmask_b32_e32 v168, v168, v169, vcc
	v_pk_mul_f32 v[152:153], v[152:153], v[168:169] op_sel_hi:[1,0]
	v_pk_mul_f32 v[154:155], v[154:155], v[168:169] op_sel_hi:[1,0]
	v_pk_mul_f32 v[170:171], v[148:149], v[168:169] op_sel_hi:[1,0]
	v_pk_mul_f32 v[180:181], v[150:151], v[168:169] op_sel_hi:[1,0]
	v_pk_mul_f32 v[160:161], v[160:161], v[168:169] op_sel_hi:[1,0]
	v_pk_mul_f32 v[162:163], v[162:163], v[168:169] op_sel_hi:[1,0]
	v_pk_mul_f32 v[182:183], v[156:157], v[168:169] op_sel_hi:[1,0]
	v_pk_mul_f32 v[168:169], v[158:159], v[168:169] op_sel_hi:[1,0]
	v_pk_mul_f32 v[150:151], v[2:3], v[154:155]
	v_pk_mul_f32 v[148:149], v[0:1], v[152:153]
	v_pk_mul_f32 v[154:155], v[6:7], v[180:181]
	v_pk_mul_f32 v[152:153], v[4:5], v[170:171]
	v_pk_mul_f32 v[158:159], v[10:11], v[162:163]
	v_pk_mul_f32 v[156:157], v[8:9], v[160:161]
	v_pk_mul_f32 v[162:163], v[14:15], v[168:169]
	v_pk_mul_f32 v[160:161], v[12:13], v[182:183]
	global_store_dwordx4 v[66:67], v[148:151], off offset:-3072 nt
	global_store_dwordx4 v[66:67], v[152:155], off offset:-2048 nt
	global_store_dwordx4 v[66:67], v[156:159], off offset:-1024 nt
	global_store_dwordx4 v[66:67], v[160:163], off nt
	v_lshl_add_u64 v[66:67], v[66:67], 0, s[14:15]
	s_cmp_eq_u64 s[16:17], 0
	s_cbranch_scc0 .Lpn_f_done
	v_add_u32_e32 v79, 32, v79
	v_cmp_ge_i32_e32 vcc, v79, v72
	s_or_b64 s[16:17], vcc, s[16:17]
	v_lshl_add_u64 v[64:65], v[64:65], 0, s[12:13]
	v_lshl_add_u64 v[100:101], v[100:101], 0, s[14:15]
	s_cmp_eq_u64 s[16:17], 0
	s_cbranch_scc0 .Lpn_f_na
	global_load_dwordx2 v[180:181], v[64:65], off nt
	global_load_dwordx2 v[168:169], v[64:65], off offset:512 nt
	global_load_dwordx4 v[152:155], v[100:101], off offset:-3072 nt
	global_load_dwordx4 v[148:151], v[100:101], off offset:-2048 nt
	global_load_dwordx2 v[170:171], v[64:65], off offset:1024 nt
	global_load_dwordx4 v[160:163], v[100:101], off offset:-1024 nt
	global_load_dwordx4 v[156:159], v[100:101], off nt
	global_load_dwordx2 v[182:183], v[64:65], off offset:1536 nt
	v_add_co_u32_e32 v184, vcc, 0xec800000, v64
	v_add_co_u32_e64 v186, s[0:1], s60, v64
	s_nop 0
	v_addc_co_u32_e32 v185, vcc, -1, v65, vcc
	v_addc_co_u32_e64 v187, s[0:1], -1, v65, s[0:1]
	global_load_dwordx2 v[184:185], v[184:185], off nt
	s_nop 0
	global_load_dwordx2 v[188:189], v[186:187], off offset:-3584 nt
	global_load_dwordx2 v[190:191], v[186:187], off offset:-3072 nt
	s_nop 0
	global_load_dwordx2 v[186:187], v[186:187], off offset:-2560 nt
	s_waitcnt vmcnt(16)
	s_branch .Lpn_f_ga
.Lpn_f_na:
	s_waitcnt vmcnt(4)
	s_branch .Lpn_f_ga
.Lpn_f_done:
	s_or_b64 exec, exec, s[16:17]
	s_cmp_lg_u32 s100, 0
	s_cbranch_scc1 .Lnt_done_f
	s_mov_b32 s100, 1
	s_mov_b64 s[16:17], 0
	v_add_u32_e32 v79, 0x700, v79
	v_add_u32_e32 v72, 0x800, v72
	s_mov_b32 vcc_lo, 0x380000
	s_mov_b32 vcc_hi, 0
	v_lshl_add_u64 v[64:65], v[64:65], 0, vcc
	s_mov_b32 vcc_lo, 0x700000
	v_lshl_add_u64 v[66:67], v[66:67], 0, vcc
	s_branch .LBB0_20
